# stack v80 + lru_item cross-wave carry prefix: seven LDS carry reads issued together, folded in the same order under a scalar wave-index test (one LDS round trip instead of up to seven)
# speedup vs baseline: 1.0086x; 1.0086x over previous
; #define LAS __attribute__((address_space(3)))
; __device__ __forceinline__ bf16_t f2bf(float f) { return (bf16_t)(pk2(f, 0.f) & 0xffffu); }
; __device__ __forceinline__ float bf2f(unsigned b) { return __uint_as_float(b << 16); }
; __device__ __forceinline__ f32x4 mfma16(bf16x8 a, bf16x8 b, f32x4 c) { return __builtin_amdgcn_mfma_f32_16x16x32_bf16(a, b, c, 0, 0, 0); }
; __device__ __forceinline__ void lds_barrier() { asm volatile("s_waitcnt lgkmcnt(0)" ::: "memory"); __builtin_amdgcn_s_barrier(); asm volatile("" ::: "memory"); }
; __device__ __forceinline__ void lru_item(const Params& p, int l, int item, LAS unsigned char* lds) {
;     ...
; #pragma unroll
;     for (int i = 0; i < 19; ++i) { const int t = t0 - 3 + i; xr[i] = (t >= 0) ? (unsigned)p.z[(Tb + (t >= 0 ? t : 0)) * ZLD + 2304 + ch] : 0u; }
;     bf16x8 wa0[4], wa1[4], wx0[4], wx1[4];
;     { const bf16_t* wap = p.waT + (((size_t)l * 4 + h) * 64 + fr) * 64 + fq * 8; const bf16_t* wxp = p.wxT + (((size_t)l * 4 + h) * 64 + fr) * 64 + fq * 8;
; #pragma unroll
;       for (int jt = 0; jt < 4; ++jt) { wa0[jt] = *(const bf16x8*)(wap + jt * 1024); wa1[jt] = *(const bf16x8*)(wap + jt * 1024 + 32); wx0[jt] = *(const bf16x8*)(wxp + jt * 1024); wx1[jt] = *(const bf16x8*)(wxp + jt * 1024 + 32); } }
;     { const float cb = p.conv_b[l * 256 + ch], cw0 = p.conv_w[(l * 4 + 0) * 256 + ch], cw1 = p.conv_w[(l * 4 + 1) * 256 + ch], cw2 = p.conv_w[(l * 4 + 2) * 256 + ch], cw3 = p.conv_w[(l * 4 + 3) * 256 + ch];
; #pragma unroll
;       for (int i = 0; i < 16; ++i) { const float xc = cb + bf2f(xr[i]) * cw0 + bf2f(xr[i + 1]) * cw1 + bf2f(xr[i + 2]) * cw2 + bf2f(xr[i + 3]) * cw3; xa[i * 72 + lane] = f2bf(xc); xf[i * 66 + lane] = xc; } }
;     lds_barrier();
;     { const bf16x8 a0 = *(const LAS bf16x8*)(xa + fr * 72 + fq * 8), a1 = *(const LAS bf16x8*)(xa + fr * 72 + 32 + fq * 8);
; #pragma unroll
;       for (int jt = 0; jt < 4; ++jt) {
;           f32x4 pa = mfma16(a0, wa0[jt], ZERO4); pa = mfma16(a1, wa1[jt], pa);
;           f32x4 px = mfma16(a0, wx0[jt], ZERO4); px = mfma16(a1, wx1[jt], px);
;           const int cj = l * 256 + h * 64 + jt * 16 + fr; const float bav = p.ba[cj], bxv = p.bx[cj], sp = p.spl[cj];
.LBB0_393:
	s_or_b64 exec, exec, s[74:75]
	s_movk_i32 s4, 0x2a00
	v_and_b32_e32 v91, 15, v1
	s_or_b32 s98, s16, s40
	v_or_b32_e32 v148, s98, v91
	v_ashrrev_i32_e32 v149, 31, v148
	v_lshlrev_b64 v[148:149], 2, v[148:149]
	v_lshl_add_u64 v[150:151], s[30:31], 0, v[148:149]
	v_lshl_add_u64 v[152:153], s[6:7], 0, v[148:149]
	v_lshl_add_u64 v[154:155], s[34:35], 0, v[148:149]
	global_load_dword v156, v[150:151], off
	global_load_dword v157, v[152:153], off
	global_load_dword v158, v[154:155], off
	global_load_dword v159, v[150:151], off offset:64
	global_load_dword v160, v[152:153], off offset:64
	global_load_dword v161, v[154:155], off offset:64
	global_load_dword v162, v[150:151], off offset:128
	global_load_dword v163, v[152:153], off offset:128
	global_load_dword v164, v[154:155], off offset:128
	global_load_dword v165, v[150:151], off offset:192
	global_load_dword v166, v[152:153], off offset:192
	global_load_dword v167, v[154:155], off offset:192
	v_mul_lo_u32 v4, v0, s4
	s_or_b32 s4, s12, s16
	v_add_u32_e32 v79, 0, v4
	v_or_b32_e32 v4, s4, v91
	v_mov_b32_e32 v5, s13
	v_lshlrev_b64 v[4:5], 7, v[4:5]
	v_lshl_add_u64 v[6:7], s[70:71], 0, v[4:5]
	v_and_b32_e32 v20, 48, v3
	v_mov_b32_e32 v21, v2
	v_lshl_add_u64 v[6:7], v[6:7], 0, v[20:21]
	v_lshl_add_u64 v[4:5], s[36:37], 0, v[4:5]
	v_add_co_u32_e32 v8, vcc, s80, v6
	v_lshl_add_u64 v[4:5], v[4:5], 0, v[20:21]
	s_nop 0
	v_addc_co_u32_e32 v9, vcc, 0, v7, vcc
	v_or_b32_e32 v100, s40, v78
	v_mov_b32_e32 v98, s17
	v_mov_b32_e32 v99, s22
	v_add_co_u32_e32 v16, vcc, s80, v4
	v_ashrrev_i32_e32 v101, 31, v100
	s_nop 0
	v_addc_co_u32_e32 v17, vcc, 0, v5, vcc
	v_lshl_add_u64 v[98:99], v[100:101], 2, v[98:99]
	global_load_dwordx4 v[60:63], v[6:7], off
	global_load_dwordx4 v[64:67], v[6:7], off offset:64
	global_load_dwordx4 v[68:71], v[4:5], off
	global_load_dwordx4 v[72:75], v[4:5], off offset:64
	global_load_dwordx4 v[44:47], v[6:7], off offset:2048
	global_load_dwordx4 v[48:51], v[6:7], off offset:2112
	global_load_dwordx4 v[52:55], v[4:5], off offset:2048
	global_load_dwordx4 v[56:59], v[4:5], off offset:2112
	global_load_dwordx4 v[28:31], v[8:9], off
	global_load_dwordx4 v[32:35], v[8:9], off offset:64
	global_load_dwordx4 v[36:39], v[16:17], off
	global_load_dwordx4 v[40:43], v[16:17], off offset:64
	s_nop 0
	global_load_dwordx4 v[4:7], v[8:9], off offset:2048
	s_nop 0
	global_load_dwordx4 v[8:11], v[8:9], off offset:2112
	s_nop 0
	global_load_dwordx4 v[12:15], v[16:17], off offset:2048
	s_nop 0
	global_load_dwordx4 v[16:19], v[16:17], off offset:2112
	v_mov_b32_e32 v96, s33
	global_load_dword v21, v[98:99], off
	v_or_b32_e32 v98, s87, v78
	v_mov_b32_e32 v97, s44
	v_ashrrev_i32_e32 v99, 31, v98
	v_lshl_add_u64 v[96:97], v[98:99], 2, v[96:97]
	global_load_dword v98, v[96:97], off
	global_load_dword v99, v[96:97], off offset:1024
	global_load_dword v100, v[96:97], off offset:2048
	s_nop 0
	global_load_dword v96, v[96:97], off offset:3072
	v_lshlrev_b32_e32 v78, 1, v3
	v_add_u32_e32 v97, v79, v78
	v_add_u32_e32 v80, v97, v78
	s_or_b32 s4, s16, s40
	s_mov_b32 s16, 0xf800000
	v_lshrrev_b32_e32 v92, 4, v3
	v_lshl_add_u32 v1, v1, 3, 0
	v_add_u32_e32 v1, 0x15000, v1
	s_waitcnt vmcnt(3)
	v_lshlrev_b32_e32 v88, 16, v88
	v_lshlrev_b32_e32 v87, 16, v87
	v_lshlrev_b32_e32 v85, 16, v85
	v_lshlrev_b32_e32 v83, 16, v83
	v_lshlrev_b32_e32 v26, 16, v26
	v_lshlrev_b32_e32 v22, 16, v22
	v_lshlrev_b32_e32 v24, 16, v24
	v_lshlrev_b32_e32 v23, 16, v23
	v_lshlrev_b32_e32 v27, 16, v27
	v_lshlrev_b32_e32 v25, 16, v25
	v_lshlrev_b32_e32 v82, 16, v82
	v_lshlrev_b32_e32 v81, 16, v81
	v_lshlrev_b32_e32 v86, 16, v86
	v_lshlrev_b32_e32 v84, 16, v84
	v_lshlrev_b32_e32 v90, 16, v90
	v_lshlrev_b32_e32 v89, 16, v89
	v_lshlrev_b32_e32 v94, 16, v94
	v_lshlrev_b32_e32 v93, 16, v93
	v_lshlrev_b32_e32 v95, 16, v95
	v_cmp_lt_i32_e32 vcc, 2, v76
	s_nop 1
	v_cndmask_b32_e32 v88, 0, v88, vcc
	v_cmp_lt_i32_e32 vcc, 1, v76
	s_nop 1
	v_cndmask_b32_e32 v87, 0, v87, vcc
	v_cmp_lt_i32_e32 vcc, 0, v76
	s_nop 1
	v_cndmask_b32_e32 v85, 0, v85, vcc
	v_fma_f32 v88, v88, v98, v21
	s_waitcnt vmcnt(2)
	v_fmac_f32_e32 v88, v87, v99
	v_fma_f32 v87, v87, v98, v21
	s_waitcnt vmcnt(1)
	v_fmac_f32_e32 v88, v85, v100
	v_fmac_f32_e32 v87, v85, v99
	s_waitcnt vmcnt(0)
	v_fmac_f32_e32 v88, v83, v96
	v_cvt_pk_bf16_f32 v101, v88, v2
	v_fmac_f32_e32 v87, v83, v100
	v_fma_f32 v85, v85, v98, v21
	ds_write_b16 v97, v101
	v_fmac_f32_e32 v87, v26, v96
	v_cvt_pk_bf16_f32 v101, v87, v2
	v_fmac_f32_e32 v85, v83, v99
	v_fma_f32 v83, v83, v98, v21
	ds_write_b16 v97, v101 offset:144
	v_add_u32_e32 v101, 0x800, v80
	v_fmac_f32_e32 v85, v26, v100
	v_fmac_f32_e32 v83, v26, v99
	ds_write2_b32 v101, v88, v87 offset0:64 offset1:130
	v_fmac_f32_e32 v85, v22, v96
	v_cvt_pk_bf16_f32 v87, v85, v2
	v_fmac_f32_e32 v83, v22, v100
	v_fma_f32 v26, v26, v98, v21
	ds_write_b16 v97, v87 offset:288
	v_fmac_f32_e32 v83, v24, v96
	v_cvt_pk_bf16_f32 v87, v83, v2
	v_fmac_f32_e32 v26, v22, v99
	v_fma_f32 v22, v22, v98, v21
	ds_write_b16 v97, v87 offset:432
	v_add_u32_e32 v87, 0xa00, v80
	v_fmac_f32_e32 v26, v24, v100
	v_fmac_f32_e32 v22, v24, v99
	ds_write2_b32 v87, v85, v83 offset0:68 offset1:134
	v_fmac_f32_e32 v26, v23, v96
	v_cvt_pk_bf16_f32 v83, v26, v2
	v_fmac_f32_e32 v22, v23, v100
	ds_write_b16 v97, v83 offset:576
	v_fmac_f32_e32 v22, v27, v96
	v_cvt_pk_bf16_f32 v83, v22, v2
	ds_write_b16 v97, v83 offset:720
	v_add_u32_e32 v83, 0xc00, v80
	ds_write2_b32 v83, v26, v22 offset0:72 offset1:138
	v_fma_f32 v22, v24, v98, v21
	v_fmac_f32_e32 v22, v23, v99
	v_fma_f32 v23, v23, v98, v21
	v_fmac_f32_e32 v22, v27, v100
	v_fmac_f32_e32 v23, v27, v99
	v_fmac_f32_e32 v22, v25, v96
	v_cvt_pk_bf16_f32 v24, v22, v2
; #define LAS __attribute__((address_space(3)))
; __device__ __forceinline__ bf16_t f2bf(float f) { return (bf16_t)(pk2(f, 0.f) & 0xffffu); }
; __device__ __forceinline__ float bf2f(unsigned b) { return __uint_as_float(b << 16); }
; __device__ __forceinline__ float fexp(float x) { return __builtin_amdgcn_exp2f(x * LOG2E); }
; __device__ __forceinline__ float sigm(float x) { return frcp(1.f + fexp(-x)); }
; __device__ __forceinline__ f32x4 mfma16(bf16x8 a, bf16x8 b, f32x4 c) { return __builtin_amdgcn_mfma_f32_16x16x32_bf16(a, b, c, 0, 0, 0); }
; __device__ __forceinline__ void lds_barrier() { asm volatile("s_waitcnt lgkmcnt(0)" ::: "memory"); __builtin_amdgcn_s_barrier(); asm volatile("" ::: "memory"); }
; __device__ __forceinline__ void lru_item(const Params& p, int l, int item, LAS unsigned char* lds) {
;     ...
;       for (int i = 0; i < 16; ++i) { const float xc = cb + bf2f(xr[i]) * cw0 + bf2f(xr[i + 1]) * cw1 + bf2f(xr[i + 2]) * cw2 + bf2f(xr[i + 3]) * cw3; xa[i * 72 + lane] = f2bf(xc); xf[i * 66 + lane] = xc; } }
;     lds_barrier();
;     { const bf16x8 a0 = *(const LAS bf16x8*)(xa + fr * 72 + fq * 8), a1 = *(const LAS bf16x8*)(xa + fr * 72 + 32 + fq * 8);
; #pragma unroll
;       for (int jt = 0; jt < 4; ++jt) {
;           f32x4 pa = mfma16(a0, wa0[jt], ZERO4); pa = mfma16(a1, wa1[jt], pa);
;           f32x4 px = mfma16(a0, wx0[jt], ZERO4); px = mfma16(a1, wx1[jt], px);
;           const int cj = l * 256 + h * 64 + jt * 16 + fr; const float bav = p.ba[cj], bxv = p.bx[cj], sp = p.spl[cj];
; #pragma unroll
;           for (int jj = 0; jj < 4; ++jj) { const int t = fq * 4 + jj; const float r = sigm(pa[jj] + bav), ig = sigm(px[jj] + bxv); const float la = -8.f * r * sp;
;               const float a = fexp(la); float mult = sqrtf(fmaxf(1.f - fexp(2.f * la), 0.f)); if (t0 + t == 0) mult = 1.f;
;               const int li = t * 66 + jt * 16 + fr; const float xcv = xf[li]; sa[li] = a; xf[li] = mult * ig * xcv; }
	v_fmac_f32_e32 v23, v25, v100
	ds_write_b16 v97, v24 offset:864
	v_fmac_f32_e32 v23, v82, v96
	v_cvt_pk_bf16_f32 v24, v23, v2
	ds_write_b16 v97, v24 offset:1008
	v_add_u32_e32 v24, 0xe00, v80
	ds_write2_b32 v24, v22, v23 offset0:76 offset1:142
	v_fma_f32 v22, v27, v98, v21
	v_fmac_f32_e32 v22, v25, v99
	v_fmac_f32_e32 v22, v82, v100
	v_fmac_f32_e32 v22, v81, v96
	v_cvt_pk_bf16_f32 v23, v22, v2
	ds_write_b16 v97, v23 offset:1152
	v_fma_f32 v23, v25, v98, v21
	v_fmac_f32_e32 v23, v82, v99
	v_fmac_f32_e32 v23, v81, v100
	v_fmac_f32_e32 v23, v86, v96
	v_cvt_pk_bf16_f32 v24, v23, v2
	ds_write_b16 v97, v24 offset:1296
	v_add_u32_e32 v24, 0x1000, v80
	ds_write2_b32 v24, v22, v23 offset0:80 offset1:146
	v_fma_f32 v22, v82, v98, v21
	v_fmac_f32_e32 v22, v81, v99
	v_fmac_f32_e32 v22, v86, v100
	v_fmac_f32_e32 v22, v84, v96
	v_cvt_pk_bf16_f32 v23, v22, v2
	ds_write_b16 v97, v23 offset:1440
	v_fma_f32 v23, v81, v98, v21
	v_fmac_f32_e32 v23, v86, v99
	v_fmac_f32_e32 v23, v84, v100
	v_fmac_f32_e32 v23, v90, v96
	v_cvt_pk_bf16_f32 v24, v23, v2
	ds_write_b16 v97, v24 offset:1584
	v_add_u32_e32 v24, 0x1200, v80
	ds_write2_b32 v24, v22, v23 offset0:84 offset1:150
	v_fma_f32 v22, v86, v98, v21
	v_fmac_f32_e32 v22, v84, v99
	v_fmac_f32_e32 v22, v90, v100
	v_fmac_f32_e32 v22, v89, v96
	v_cvt_pk_bf16_f32 v23, v22, v2
	ds_write_b16 v97, v23 offset:1728
	v_fma_f32 v23, v84, v98, v21
	v_fmac_f32_e32 v23, v90, v99
	v_fmac_f32_e32 v23, v89, v100
	v_fmac_f32_e32 v23, v94, v96
	v_cvt_pk_bf16_f32 v24, v23, v2
	ds_write_b16 v97, v24 offset:1872
	v_add_u32_e32 v24, 0x1400, v80
	ds_write2_b32 v24, v22, v23 offset0:88 offset1:154
	v_fma_f32 v22, v90, v98, v21
	v_fmac_f32_e32 v22, v89, v99
	v_fmac_f32_e32 v21, v89, v98
	v_fmac_f32_e32 v22, v94, v100
	v_fmac_f32_e32 v21, v94, v99
	v_fmac_f32_e32 v22, v93, v96
	v_cvt_pk_bf16_f32 v23, v22, v2
	v_fmac_f32_e32 v21, v93, v100
	ds_write_b16 v97, v23 offset:2016
	v_fmac_f32_e32 v21, v95, v96
	v_cvt_pk_bf16_f32 v23, v21, v2
	ds_write_b16 v97, v23 offset:2160
	v_add_u32_e32 v23, 0x1600, v80
	ds_write2_b32 v23, v22, v21 offset0:92 offset1:158
	v_mul_u32_u24_e32 v21, 0x90, v91
	s_waitcnt lgkmcnt(0)
	s_barrier
	v_add3_u32 v24, v79, v21, v20
	ds_read_b128 v[20:23], v24
	ds_read_b128 v[24:27], v24 offset:64
	s_waitcnt lgkmcnt(1)
	v_mfma_f32_16x16x32_bf16 v[60:63], v[20:23], v[60:63], 0
	v_or_b32_e32 v86, s4, v91
	v_ashrrev_i32_e32 v87, 31, v86
	s_waitcnt lgkmcnt(0)
	v_mfma_f32_16x16x32_bf16 v[82:85], v[24:27], v[64:67], v[60:63]
	v_mfma_f32_16x16x32_bf16 v[60:63], v[20:23], v[68:71], 0
	v_mfma_f32_16x16x32_bf16 v[70:73], v[24:27], v[72:75], v[60:63]
	v_mfma_f32_16x16x32_bf16 v[44:47], v[20:23], v[44:47], 0
	s_nop 5
	v_lshlrev_b64 v[60:61], 2, v[86:87]
	v_lshl_add_u64 v[64:65], s[30:31], 0, v[60:61]
	v_lshl_add_u64 v[62:63], s[6:7], 0, v[60:61]
	v_lshl_add_u64 v[60:61], s[34:35], 0, v[60:61]
	v_mfma_f32_16x16x32_bf16 v[48:51], v[24:27], v[48:51], v[44:47]
	s_waitcnt vmcnt(0)
	v_mov_b32_e32 v81, v156
	v_mov_b32_e32 v86, v157
	v_mov_b32_e32 v87, v158
	v_add_f32_e32 v66, v82, v81
	v_mul_f32_e32 v66, 0xbfb8aa3b, v66
	v_exp_f32_e32 v66, v66
	s_waitcnt vmcnt(1)
	v_add_f32_e32 v67, v70, v86
	v_mul_f32_e32 v67, 0xbfb8aa3b, v67
	v_exp_f32_e32 v67, v67
	v_add_f32_e32 v66, 1.0, v66
	v_rcp_f32_e32 v66, v66
	v_mfma_f32_16x16x32_bf16 v[44:47], v[20:23], v[52:55], 0
	v_add_f32_e32 v67, 1.0, v67
	v_rcp_f32_e32 v68, v67
	v_mul_f32_e32 v66, 0xc1000000, v66
	s_waitcnt vmcnt(0)
	v_mul_f32_e32 v66, v87, v66
	v_mul_f32_e32 v67, 0x3fb8aa3b, v66
	v_add_f32_e32 v66, v66, v66
	v_mul_f32_e32 v66, 0x3fb8aa3b, v66
	v_exp_f32_e32 v66, v66
	v_exp_f32_e32 v69, v67
	v_mfma_f32_16x16x32_bf16 v[44:47], v[24:27], v[56:59], v[44:47]
	v_sub_f32_e32 v66, 1.0, v66
	v_max_f32_e32 v66, 0, v66
	v_mfma_f32_16x16x32_bf16 v[28:31], v[20:23], v[28:31], 0
	v_sqrt_f32_e32 v67, v66
	v_mfma_f32_16x16x32_bf16 v[32:35], v[24:27], v[32:35], v[28:31]
	v_add_u32_e32 v70, -1, v67
	v_fma_f32 v74, -v70, v67, v66
	v_cmp_ge_f32_e64 s[4:5], 0, v74
	v_add_u32_e32 v74, 1, v67
	v_mfma_f32_16x16x32_bf16 v[28:31], v[20:23], v[36:39], 0
	v_cndmask_b32_e64 v70, v67, v70, s[4:5]
	v_fma_f32 v67, -v74, v67, v66
	v_cmp_lt_f32_e64 s[4:5], 0, v67
	v_mfma_f32_16x16x32_bf16 v[28:31], v[24:27], v[40:43], v[28:31]
	s_nop 0
	v_cndmask_b32_e64 v67, v70, v74, s[4:5]
	s_movk_i32 s4, 0x108
	v_mfma_f32_16x16x32_bf16 v[4:7], v[20:23], v[4:7], 0
	v_mov_b32_e32 v66, v67
	v_or_b32_e32 v67, v76, v92
	v_cmp_eq_u32_e32 vcc, 0, v67
	v_mfma_f32_16x16x32_bf16 v[8:11], v[24:27], v[8:11], v[4:7]
	s_nop 0
	v_cndmask_b32_e64 v70, v66, 1.0, vcc
	v_mad_u32_u24 v66, v92, s4, v91
	v_lshl_add_u32 v74, v66, 2, v79
	v_add_u32_e32 v75, 0x800, v74
	ds_read2_b32 v[66:67], v75 offset0:64 offset1:80
	v_mul_f32_e32 v68, v68, v70
	ds_write_b32 v74, v69 offset:6528
	v_mfma_f32_16x16x32_bf16 v[4:7], v[20:23], v[12:15], 0
	s_waitcnt lgkmcnt(1)
	v_mul_f32_e32 v66, v66, v68
	ds_write_b32 v74, v66 offset:2304
	v_add_f32_e32 v66, v83, v81
	v_mul_f32_e32 v66, 0xbfb8aa3b, v66
	v_exp_f32_e32 v66, v66
	v_add_f32_e32 v68, v71, v86
	v_mul_f32_e32 v68, 0xbfb8aa3b, v68
	v_exp_f32_e32 v68, v68
	v_add_f32_e32 v66, 1.0, v66
	v_rcp_f32_e32 v66, v66
	v_mfma_f32_16x16x32_bf16 v[4:7], v[24:27], v[16:19], v[4:7]
	v_add_f32_e32 v68, 1.0, v68
	v_rcp_f32_e32 v70, v68
	v_mul_f32_e32 v66, 0xc1000000, v66
	v_mul_f32_e32 v66, v87, v66
	v_mul_f32_e32 v68, 0x3fb8aa3b, v66
	v_add_f32_e32 v66, v66, v66
	v_mul_f32_e32 v66, 0x3fb8aa3b, v66
	v_exp_f32_e32 v66, v66
	v_exp_f32_e32 v71, v68
	v_sub_f32_e32 v66, 1.0, v66
	v_max_f32_e32 v66, 0, v66
	s_nop 0
	v_sqrt_f32_e32 v68, v66
	s_nop 0
	v_add_u32_e32 v69, -1, v68
	v_fma_f32 v76, -v69, v68, v66
	v_cmp_ge_f32_e64 s[6:7], 0, v76
	v_add_u32_e32 v76, 1, v68
	s_nop 0
	v_cndmask_b32_e64 v69, v68, v69, s[6:7]
	v_fma_f32 v68, -v76, v68, v66
	v_cmp_lt_f32_e64 s[6:7], 0, v68
	s_nop 1
	v_cndmask_b32_e64 v68, v69, v76, s[6:7]
	s_nop 1
	v_mov_b32_e32 v66, v68
	ds_read2_b32 v[68:69], v75 offset0:130 offset1:146
	v_mul_f32_e32 v66, v70, v66
	ds_write_b32 v74, v71 offset:6792
	s_waitcnt lgkmcnt(1)
; __device__ __forceinline__ float fexp(float x) { return __builtin_amdgcn_exp2f(x * LOG2E); }
; __device__ __forceinline__ float sigm(float x) { return frcp(1.f + fexp(-x)); }
; __device__ __forceinline__ f32x4 mfma16(bf16x8 a, bf16x8 b, f32x4 c) { return __builtin_amdgcn_mfma_f32_16x16x32_bf16(a, b, c, 0, 0, 0); }
; __device__ __forceinline__ void lru_item(const Params& p, int l, int item, LAS unsigned char* lds) {
;     ...
;       for (int jt = 0; jt < 4; ++jt) {
;           f32x4 pa = mfma16(a0, wa0[jt], ZERO4); pa = mfma16(a1, wa1[jt], pa);
;           f32x4 px = mfma16(a0, wx0[jt], ZERO4); px = mfma16(a1, wx1[jt], px);
;           const int cj = l * 256 + h * 64 + jt * 16 + fr; const float bav = p.ba[cj], bxv = p.bx[cj], sp = p.spl[cj];
; #pragma unroll
;           for (int jj = 0; jj < 4; ++jj) { const int t = fq * 4 + jj; const float r = sigm(pa[jj] + bav), ig = sigm(px[jj] + bxv); const float la = -8.f * r * sp;
;               const float a = fexp(la); float mult = sqrtf(fmaxf(1.f - fexp(2.f * la), 0.f)); if (t0 + t == 0) mult = 1.f;
;               const int li = t * 66 + jt * 16 + fr; const float xcv = xf[li]; sa[li] = a; xf[li] = mult * ig * xcv; }
	v_mul_f32_e32 v66, v68, v66
	ds_write_b32 v74, v66 offset:2568
	v_add_f32_e32 v66, v84, v81
	v_mul_f32_e32 v66, 0xbfb8aa3b, v66
	v_exp_f32_e32 v66, v66
	v_add_f32_e32 v68, v72, v86
	v_mul_f32_e32 v68, 0xbfb8aa3b, v68
	v_exp_f32_e32 v68, v68
	v_add_f32_e32 v66, 1.0, v66
	v_rcp_f32_e32 v66, v66
	v_add_f32_e32 v68, 1.0, v68
	v_rcp_f32_e32 v68, v68
	v_mul_f32_e32 v66, 0xc1000000, v66
	v_mul_f32_e32 v66, v87, v66
	v_mul_f32_e32 v70, 0x3fb8aa3b, v66
	v_add_f32_e32 v66, v66, v66
	v_mul_f32_e32 v66, 0x3fb8aa3b, v66
	v_exp_f32_e32 v66, v66
	v_exp_f32_e32 v72, v70
	v_sub_f32_e32 v66, 1.0, v66
	v_max_f32_e32 v66, 0, v66
	s_nop 0
	v_sqrt_f32_e32 v70, v66
	s_nop 0
	v_add_u32_e32 v71, -1, v70
	v_fma_f32 v76, -v71, v70, v66
	v_cmp_ge_f32_e64 s[6:7], 0, v76
	v_add_u32_e32 v76, 1, v70
	s_nop 0
	v_cndmask_b32_e64 v71, v70, v71, s[6:7]
	v_fma_f32 v70, -v76, v70, v66
	v_cmp_lt_f32_e64 s[6:7], 0, v70
	s_nop 1
	v_cndmask_b32_e64 v70, v71, v76, s[6:7]
	s_nop 1
	v_mov_b32_e32 v66, v70
	ds_read2_b32 v[70:71], v75 offset0:196 offset1:212
	v_mul_f32_e32 v66, v68, v66
	v_add_f32_e32 v68, v73, v86
	v_mul_f32_e32 v68, 0xbfb8aa3b, v68
	v_exp_f32_e32 v68, v68
	s_waitcnt lgkmcnt(0)
	v_mul_f32_e32 v66, v70, v66
	ds_write_b32 v74, v66 offset:2832
	v_add_f32_e32 v66, v85, v81
	v_mul_f32_e32 v66, 0xbfb8aa3b, v66
	v_exp_f32_e32 v66, v66
	v_add_f32_e32 v68, 1.0, v68
	v_rcp_f32_e32 v70, v68
	ds_write_b32 v74, v72 offset:7056
	v_add_f32_e32 v66, 1.0, v66
	v_rcp_f32_e32 v66, v66
	s_nop 0
	v_mul_f32_e32 v66, 0xc1000000, v66
	v_mul_f32_e32 v66, v87, v66
	v_mul_f32_e32 v68, 0x3fb8aa3b, v66
	v_add_f32_e32 v66, v66, v66
	v_mul_f32_e32 v66, 0x3fb8aa3b, v66
	v_exp_f32_e32 v66, v66
	v_exp_f32_e32 v68, v68
	v_sub_f32_e32 v66, 1.0, v66
	v_max_f32_e32 v66, 0, v66
	s_nop 0
	v_sqrt_f32_e32 v72, v66
	s_nop 0
	v_add_u32_e32 v73, -1, v72
	v_fma_f32 v76, -v73, v72, v66
	v_cmp_ge_f32_e64 s[6:7], 0, v76
	v_add_u32_e32 v76, 1, v72
	s_nop 0
	v_cndmask_b32_e64 v73, v72, v73, s[6:7]
	v_fma_f32 v72, -v76, v72, v66
	v_cmp_lt_f32_e64 s[6:7], 0, v72
	s_nop 1
	v_cndmask_b32_e64 v72, v73, v76, s[6:7]
	s_nop 1
	v_mov_b32_e32 v76, v72
	v_add_u32_e32 v66, 0xc00, v74
	ds_read2_b32 v[72:73], v66 offset0:6 offset1:22
	v_mov_b32_e32 v52, v159
	v_mov_b32_e32 v53, v160
	v_mov_b32_e32 v54, v161
	v_mul_f32_e32 v70, v70, v76
	s_waitcnt lgkmcnt(0)
	v_mul_f32_e32 v70, v72, v70
	s_waitcnt vmcnt(2)
	v_add_f32_e32 v48, v48, v52
	v_mul_f32_e32 v48, 0xbfb8aa3b, v48
	v_exp_f32_e32 v48, v48
	s_waitcnt vmcnt(1)
	v_add_f32_e32 v44, v44, v53
	v_mul_f32_e32 v44, 0xbfb8aa3b, v44
	v_exp_f32_e32 v44, v44
	v_add_f32_e32 v48, 1.0, v48
	v_rcp_f32_e32 v48, v48
	v_add_f32_e32 v45, v45, v53
	v_add_f32_e32 v44, 1.0, v44
	v_rcp_f32_e32 v44, v44
	v_mul_f32_e32 v48, 0xc1000000, v48
	s_waitcnt vmcnt(0)
	v_mul_f32_e32 v48, v54, v48
	v_mul_f32_e32 v55, 0x3fb8aa3b, v48
	v_add_f32_e32 v48, v48, v48
	v_mul_f32_e32 v48, 0x3fb8aa3b, v48
	v_exp_f32_e32 v48, v48
	v_exp_f32_e32 v55, v55
	v_mul_f32_e32 v45, 0xbfb8aa3b, v45
	v_exp_f32_e32 v45, v45
	v_sub_f32_e32 v48, 1.0, v48
	v_max_f32_e32 v48, 0, v48
	ds_write_b32 v74, v55 offset:6592
	v_sqrt_f32_e32 v56, v48
	v_add_f32_e32 v45, 1.0, v45
	v_rcp_f32_e32 v45, v45
	v_add_u32_e32 v57, -1, v56
	v_fma_f32 v58, -v57, v56, v48
	v_cmp_ge_f32_e64 s[6:7], 0, v58
	v_add_u32_e32 v58, 1, v56
	s_nop 0
	v_cndmask_b32_e64 v57, v56, v57, s[6:7]
	v_fma_f32 v56, -v58, v56, v48
	v_cmp_lt_f32_e64 s[6:7], 0, v56
	s_nop 1
	v_cndmask_b32_e64 v56, v57, v58, s[6:7]
	s_nop 1
	v_mov_b32_e32 v48, v56
	v_cndmask_b32_e64 v48, v48, 1.0, vcc
	v_mul_f32_e32 v44, v44, v48
	v_mul_f32_e32 v48, v67, v44
	v_add_f32_e32 v44, v49, v52
	v_mul_f32_e32 v44, 0xbfb8aa3b, v44
	v_exp_f32_e32 v44, v44
	s_nop 0
	v_add_f32_e32 v44, 1.0, v44
	v_rcp_f32_e32 v44, v44
	s_nop 0
	v_mul_f32_e32 v44, 0xc1000000, v44
	v_mul_f32_e32 v44, v54, v44
	v_mul_f32_e32 v49, 0x3fb8aa3b, v44
	v_add_f32_e32 v44, v44, v44
	v_mul_f32_e32 v44, 0x3fb8aa3b, v44
	v_exp_f32_e32 v44, v44
	v_exp_f32_e32 v49, v49
	v_sub_f32_e32 v44, 1.0, v44
	v_max_f32_e32 v44, 0, v44
	ds_write_b32 v74, v49 offset:6856
	v_sqrt_f32_e32 v55, v44
	s_nop 0
	v_add_u32_e32 v56, -1, v55
	v_fma_f32 v57, -v56, v55, v44
	v_cmp_ge_f32_e64 s[6:7], 0, v57
	v_add_u32_e32 v57, 1, v55
	s_nop 0
	v_cndmask_b32_e64 v56, v55, v56, s[6:7]
	v_fma_f32 v55, -v57, v55, v44
	v_cmp_lt_f32_e64 s[6:7], 0, v55
	s_nop 1
	v_cndmask_b32_e64 v55, v56, v57, s[6:7]
	s_nop 1
	v_mov_b32_e32 v44, v55
	v_mul_f32_e32 v44, v45, v44
	v_mul_f32_e32 v44, v69, v44
	ds_write_b32 v74, v44 offset:2632
	v_add_f32_e32 v44, v50, v52
	v_mul_f32_e32 v44, 0xbfb8aa3b, v44
	v_exp_f32_e32 v44, v44
	v_add_f32_e32 v45, v46, v53
	v_mul_f32_e32 v45, 0xbfb8aa3b, v45
	v_exp_f32_e32 v45, v45
	v_add_f32_e32 v44, 1.0, v44
	v_rcp_f32_e32 v44, v44
	v_add_f32_e32 v45, 1.0, v45
	v_rcp_f32_e32 v45, v45
	v_mul_f32_e32 v44, 0xc1000000, v44
	v_mul_f32_e32 v44, v54, v44
	v_mul_f32_e32 v46, 0x3fb8aa3b, v44
	v_add_f32_e32 v44, v44, v44
	v_mul_f32_e32 v44, 0x3fb8aa3b, v44
	v_exp_f32_e32 v44, v44
	v_exp_f32_e32 v46, v46
	v_sub_f32_e32 v44, 1.0, v44
	v_max_f32_e32 v44, 0, v44
	ds_write_b32 v74, v46 offset:7120
	v_sqrt_f32_e32 v49, v44
	s_nop 0
	v_add_u32_e32 v50, -1, v49
	v_fma_f32 v55, -v50, v49, v44
	v_cmp_ge_f32_e64 s[6:7], 0, v55
	v_add_u32_e32 v55, 1, v49
	s_nop 0
	v_cndmask_b32_e64 v50, v49, v50, s[6:7]
	v_fma_f32 v49, -v55, v49, v44
	v_cmp_lt_f32_e64 s[6:7], 0, v49
	s_nop 1
	v_cndmask_b32_e64 v49, v50, v55, s[6:7]
	s_nop 1
	v_mov_b32_e32 v44, v49
	v_mul_f32_e32 v44, v45, v44
	v_mul_f32_e32 v44, v71, v44
	ds_write_b32 v74, v44 offset:2896
	v_add_f32_e32 v44, v51, v52
	v_mul_f32_e32 v44, 0xbfb8aa3b, v44
	v_exp_f32_e32 v44, v44
	v_add_f32_e32 v45, v47, v53
	v_mul_f32_e32 v45, 0xbfb8aa3b, v45
	v_exp_f32_e32 v45, v45
	v_add_f32_e32 v44, 1.0, v44
	v_rcp_f32_e32 v44, v44
	v_add_f32_e32 v45, 1.0, v45
	v_rcp_f32_e32 v45, v45
	v_mul_f32_e32 v44, 0xc1000000, v44
	v_mul_f32_e32 v44, v54, v44
	v_mul_f32_e32 v46, 0x3fb8aa3b, v44
	v_add_f32_e32 v44, v44, v44
	v_mul_f32_e32 v44, 0x3fb8aa3b, v44
	v_exp_f32_e32 v44, v44
	v_exp_f32_e32 v46, v46
	v_sub_f32_e32 v44, 1.0, v44
	v_max_f32_e32 v44, 0, v44
	s_nop 0
	v_sqrt_f32_e32 v47, v44
	s_nop 0
	v_add_u32_e32 v49, -1, v47
	v_fma_f32 v50, -v49, v47, v44
	v_cmp_ge_f32_e64 s[6:7], 0, v50
	v_add_u32_e32 v50, 1, v47
	s_nop 0
	v_cndmask_b32_e64 v49, v47, v49, s[6:7]
	v_fma_f32 v47, -v50, v47, v44
	v_cmp_lt_f32_e64 s[6:7], 0, v47
	s_nop 1
	v_cndmask_b32_e64 v47, v49, v50, s[6:7]
	s_nop 1
	v_mul_f32_e32 v45, v45, v47
	v_add_u32_e32 v44, 0x1c00, v74
	v_mul_f32_e32 v45, v73, v45
	ds_write2_b32 v44, v68, v46 offset0:38 offset1:54
	ds_write2_b32 v66, v70, v45 offset0:6 offset1:22
	v_mov_b32_e32 v40, v162
	v_mov_b32_e32 v41, v163
	v_mov_b32_e32 v42, v164
	s_waitcnt vmcnt(2)
; __device__ __forceinline__ float fexp(float x) { return __builtin_amdgcn_exp2f(x * LOG2E); }
; __device__ __forceinline__ float sigm(float x) { return frcp(1.f + fexp(-x)); }
; __device__ __forceinline__ f32x4 mfma16(bf16x8 a, bf16x8 b, f32x4 c) { return __builtin_amdgcn_mfma_f32_16x16x32_bf16(a, b, c, 0, 0, 0); }
; __device__ __forceinline__ void lru_item(const Params& p, int l, int item, LAS unsigned char* lds) {
;     ...
;       for (int jt = 0; jt < 4; ++jt) {
;           f32x4 pa = mfma16(a0, wa0[jt], ZERO4); pa = mfma16(a1, wa1[jt], pa);
;           f32x4 px = mfma16(a0, wx0[jt], ZERO4); px = mfma16(a1, wx1[jt], px);
;           const int cj = l * 256 + h * 64 + jt * 16 + fr; const float bav = p.ba[cj], bxv = p.bx[cj], sp = p.spl[cj];
; #pragma unroll
;           for (int jj = 0; jj < 4; ++jj) { const int t = fq * 4 + jj; const float r = sigm(pa[jj] + bav), ig = sigm(px[jj] + bxv); const float la = -8.f * r * sp;
;               const float a = fexp(la); float mult = sqrtf(fmaxf(1.f - fexp(2.f * la), 0.f)); if (t0 + t == 0) mult = 1.f;
;               const int li = t * 66 + jt * 16 + fr; const float xcv = xf[li]; sa[li] = a; xf[li] = mult * ig * xcv; }
	v_add_f32_e32 v32, v32, v40
	v_mul_f32_e32 v32, 0xbfb8aa3b, v32
	v_exp_f32_e32 v32, v32
	s_waitcnt vmcnt(1)
	v_add_f32_e32 v28, v28, v41
	v_mul_f32_e32 v28, 0xbfb8aa3b, v28
	v_exp_f32_e32 v28, v28
	v_add_f32_e32 v32, 1.0, v32
	v_rcp_f32_e32 v32, v32
	v_add_f32_e32 v29, v29, v41
	v_add_f32_e32 v28, 1.0, v28
	v_rcp_f32_e32 v28, v28
	v_mul_f32_e32 v32, 0xc1000000, v32
	s_waitcnt vmcnt(0)
	v_mul_f32_e32 v32, v42, v32
	v_mul_f32_e32 v36, 0x3fb8aa3b, v32
	v_add_f32_e32 v32, v32, v32
	v_mul_f32_e32 v32, 0x3fb8aa3b, v32
	v_exp_f32_e32 v32, v32
	v_exp_f32_e32 v36, v36
	v_mul_f32_e32 v29, 0xbfb8aa3b, v29
	v_exp_f32_e32 v29, v29
	v_sub_f32_e32 v32, 1.0, v32
	v_max_f32_e32 v32, 0, v32
	ds_write_b32 v74, v36 offset:6656
	v_sqrt_f32_e32 v37, v32
	v_add_f32_e32 v29, 1.0, v29
	v_rcp_f32_e32 v29, v29
	v_add_u32_e32 v38, -1, v37
	v_fma_f32 v39, -v38, v37, v32
	v_cmp_ge_f32_e64 s[6:7], 0, v39
	v_add_u32_e32 v39, 1, v37
	s_nop 0
	v_cndmask_b32_e64 v38, v37, v38, s[6:7]
	v_fma_f32 v37, -v39, v37, v32
	v_cmp_lt_f32_e64 s[6:7], 0, v37
	s_nop 1
	v_cndmask_b32_e64 v37, v38, v39, s[6:7]
	ds_read2_b32 v[38:39], v75 offset0:96 offset1:112
	s_nop 1
	v_mov_b32_e32 v32, v37
	v_cndmask_b32_e64 v32, v32, 1.0, vcc
	v_mul_f32_e32 v28, v28, v32
	s_waitcnt lgkmcnt(0)
	v_mul_f32_e32 v28, v38, v28
	ds_write2_b32 v75, v48, v28 offset0:80 offset1:96
	v_add_f32_e32 v28, v33, v40
	v_mul_f32_e32 v28, 0xbfb8aa3b, v28
	v_exp_f32_e32 v28, v28
	s_nop 0
	v_add_f32_e32 v28, 1.0, v28
	v_rcp_f32_e32 v28, v28
	s_nop 0
	v_mul_f32_e32 v28, 0xc1000000, v28
	v_mul_f32_e32 v28, v42, v28
	v_mul_f32_e32 v32, 0x3fb8aa3b, v28
	v_add_f32_e32 v28, v28, v28
	v_mul_f32_e32 v28, 0x3fb8aa3b, v28
	v_exp_f32_e32 v28, v28
	v_exp_f32_e32 v32, v32
	v_sub_f32_e32 v28, 1.0, v28
	v_max_f32_e32 v28, 0, v28
	s_nop 0
	v_sqrt_f32_e32 v33, v28
	s_nop 0
	v_add_u32_e32 v36, -1, v33
	v_fma_f32 v37, -v36, v33, v28
	v_cmp_ge_f32_e64 s[6:7], 0, v37
	v_add_u32_e32 v37, 1, v33
	s_nop 0
	v_cndmask_b32_e64 v36, v33, v36, s[6:7]
	v_fma_f32 v33, -v37, v33, v28
	v_cmp_lt_f32_e64 s[6:7], 0, v33
	s_nop 1
	v_cndmask_b32_e64 v33, v36, v37, s[6:7]
	ds_read2_b32 v[36:37], v75 offset0:162 offset1:178
	ds_write_b32 v74, v32 offset:6920
	s_nop 0
	v_mov_b32_e32 v28, v33
	v_mul_f32_e32 v28, v29, v28
	s_waitcnt lgkmcnt(1)
	v_mul_f32_e32 v28, v36, v28
	ds_write_b32 v74, v28 offset:2696
	v_add_f32_e32 v28, v34, v40
	v_mul_f32_e32 v28, 0xbfb8aa3b, v28
	v_exp_f32_e32 v28, v28
	v_add_f32_e32 v29, v30, v41
	v_mul_f32_e32 v29, 0xbfb8aa3b, v29
	v_exp_f32_e32 v29, v29
	v_add_f32_e32 v28, 1.0, v28
	v_rcp_f32_e32 v28, v28
	v_add_f32_e32 v29, 1.0, v29
	v_rcp_f32_e32 v29, v29
	v_mul_f32_e32 v28, 0xc1000000, v28
	v_mul_f32_e32 v28, v42, v28
	v_mul_f32_e32 v30, 0x3fb8aa3b, v28
	v_add_f32_e32 v28, v28, v28
	v_mul_f32_e32 v28, 0x3fb8aa3b, v28
	v_exp_f32_e32 v28, v28
	v_exp_f32_e32 v30, v30
	v_sub_f32_e32 v28, 1.0, v28
	v_max_f32_e32 v28, 0, v28
	s_nop 0
	v_sqrt_f32_e32 v32, v28
	s_nop 0
	v_add_u32_e32 v33, -1, v32
	v_fma_f32 v34, -v33, v32, v28
	v_cmp_ge_f32_e64 s[6:7], 0, v34
	v_add_u32_e32 v34, 1, v32
	s_nop 0
	v_cndmask_b32_e64 v33, v32, v33, s[6:7]
	v_fma_f32 v32, -v34, v32, v28
	v_cmp_lt_f32_e64 s[6:7], 0, v32
	s_nop 1
	v_cndmask_b32_e64 v32, v33, v34, s[6:7]
	s_nop 1
	v_mov_b32_e32 v28, v32
	ds_read2_b32 v[32:33], v75 offset0:228 offset1:244
	v_mul_f32_e32 v28, v29, v28
	v_add_f32_e32 v29, v31, v41
	v_mul_f32_e32 v29, 0xbfb8aa3b, v29
	v_exp_f32_e32 v29, v29
	s_waitcnt lgkmcnt(0)
	v_mul_f32_e32 v28, v32, v28
	ds_write_b32 v74, v28 offset:2960
	v_add_f32_e32 v28, v35, v40
	v_mul_f32_e32 v28, 0xbfb8aa3b, v28
	v_exp_f32_e32 v28, v28
	v_add_f32_e32 v29, 1.0, v29
	v_rcp_f32_e32 v31, v29
	ds_write_b32 v74, v30 offset:7184
	v_add_f32_e32 v28, 1.0, v28
	v_rcp_f32_e32 v28, v28
	s_nop 0
	v_mul_f32_e32 v28, 0xc1000000, v28
	v_mul_f32_e32 v28, v42, v28
	v_mul_f32_e32 v29, 0x3fb8aa3b, v28
	v_add_f32_e32 v28, v28, v28
	v_mul_f32_e32 v28, 0x3fb8aa3b, v28
	v_exp_f32_e32 v28, v28
	v_exp_f32_e32 v30, v29
	v_sub_f32_e32 v28, 1.0, v28
	v_max_f32_e32 v28, 0, v28
	s_nop 0
	v_sqrt_f32_e32 v29, v28
	s_nop 0
	v_add_u32_e32 v32, -1, v29
	v_fma_f32 v34, -v32, v29, v28
	v_cmp_ge_f32_e64 s[6:7], 0, v34
	v_add_u32_e32 v34, 1, v29
	s_nop 0
	v_cndmask_b32_e64 v32, v29, v32, s[6:7]
	v_fma_f32 v29, -v34, v29, v28
	v_cmp_lt_f32_e64 s[6:7], 0, v29
	s_nop 1
	v_cndmask_b32_e64 v29, v32, v34, s[6:7]
	s_nop 1
	v_mov_b32_e32 v32, v29
	ds_read2_b32 v[28:29], v66 offset0:38 offset1:54
	v_mov_b32_e32 v12, v165
	v_mov_b32_e32 v13, v166
	v_mov_b32_e32 v14, v167
	v_mul_f32_e32 v31, v31, v32
	s_waitcnt lgkmcnt(0)
	v_mul_f32_e32 v28, v28, v31
	s_waitcnt vmcnt(2)
	v_add_f32_e32 v8, v8, v12
	v_mul_f32_e32 v8, 0xbfb8aa3b, v8
	v_exp_f32_e32 v8, v8
	s_waitcnt vmcnt(1)
	v_add_f32_e32 v4, v4, v13
	v_mul_f32_e32 v4, 0xbfb8aa3b, v4
	v_exp_f32_e32 v4, v4
	v_add_f32_e32 v8, 1.0, v8
	v_rcp_f32_e32 v8, v8
	v_add_f32_e32 v5, v5, v13
	v_add_f32_e32 v4, 1.0, v4
	v_rcp_f32_e32 v4, v4
	v_mul_f32_e32 v8, 0xc1000000, v8
	s_waitcnt vmcnt(0)
; __device__ __forceinline__ float fexp(float x) { return __builtin_amdgcn_exp2f(x * LOG2E); }
; __device__ __forceinline__ float sigm(float x) { return frcp(1.f + fexp(-x)); }
; __device__ __forceinline__ f32x4 mfma16(bf16x8 a, bf16x8 b, f32x4 c) { return __builtin_amdgcn_mfma_f32_16x16x32_bf16(a, b, c, 0, 0, 0); }
; __device__ __forceinline__ void lds_barrier() { asm volatile("s_waitcnt lgkmcnt(0)" ::: "memory"); __builtin_amdgcn_s_barrier(); asm volatile("" ::: "memory"); }
; __device__ __forceinline__ void lru_item(const Params& p, int l, int item, LAS unsigned char* lds) {
;     ...
;       for (int jt = 0; jt < 4; ++jt) {
;           f32x4 pa = mfma16(a0, wa0[jt], ZERO4); pa = mfma16(a1, wa1[jt], pa);
;           f32x4 px = mfma16(a0, wx0[jt], ZERO4); px = mfma16(a1, wx1[jt], px);
;           const int cj = l * 256 + h * 64 + jt * 16 + fr; const float bav = p.ba[cj], bxv = p.bx[cj], sp = p.spl[cj];
; #pragma unroll
;           for (int jj = 0; jj < 4; ++jj) { const int t = fq * 4 + jj; const float r = sigm(pa[jj] + bav), ig = sigm(px[jj] + bxv); const float la = -8.f * r * sp;
;               const float a = fexp(la); float mult = sqrtf(fmaxf(1.f - fexp(2.f * la), 0.f)); if (t0 + t == 0) mult = 1.f;
;               const int li = t * 66 + jt * 16 + fr; const float xcv = xf[li]; sa[li] = a; xf[li] = mult * ig * xcv; }
;       } }
;     lds_barrier();
	v_mul_f32_e32 v8, v14, v8
	v_mul_f32_e32 v15, 0x3fb8aa3b, v8
	v_add_f32_e32 v8, v8, v8
	v_mul_f32_e32 v8, 0x3fb8aa3b, v8
	v_exp_f32_e32 v8, v8
	v_exp_f32_e32 v15, v15
	v_mul_f32_e32 v5, 0xbfb8aa3b, v5
	v_exp_f32_e32 v5, v5
	v_sub_f32_e32 v8, 1.0, v8
	v_max_f32_e32 v8, 0, v8
	ds_write_b32 v74, v15 offset:6720
	v_sqrt_f32_e32 v16, v8
	v_add_f32_e32 v5, 1.0, v5
	v_rcp_f32_e32 v5, v5
	v_add_u32_e32 v17, -1, v16
	v_fma_f32 v18, -v17, v16, v8
	v_cmp_ge_f32_e64 s[6:7], 0, v18
	v_add_u32_e32 v18, 1, v16
	s_nop 0
	v_cndmask_b32_e64 v17, v16, v17, s[6:7]
	v_fma_f32 v16, -v18, v16, v8
	v_cmp_lt_f32_e64 s[6:7], 0, v16
	s_nop 1
	v_cndmask_b32_e64 v16, v17, v18, s[6:7]
	s_nop 1
	v_mov_b32_e32 v8, v16
	v_cndmask_b32_e64 v8, v8, 1.0, vcc
	v_mul_f32_e32 v4, v4, v8
	v_mul_f32_e32 v4, v39, v4
	ds_write_b32 v74, v4 offset:2496
	v_add_f32_e32 v4, v9, v12
	v_mul_f32_e32 v4, 0xbfb8aa3b, v4
	v_exp_f32_e32 v4, v4
	s_nop 0
	v_add_f32_e32 v4, 1.0, v4
	v_rcp_f32_e32 v4, v4
	s_nop 0
	v_mul_f32_e32 v4, 0xc1000000, v4
	v_mul_f32_e32 v4, v14, v4
	v_mul_f32_e32 v8, 0x3fb8aa3b, v4
	v_add_f32_e32 v4, v4, v4
	v_mul_f32_e32 v4, 0x3fb8aa3b, v4
	v_exp_f32_e32 v4, v4
	v_exp_f32_e32 v8, v8
	v_sub_f32_e32 v4, 1.0, v4
	v_max_f32_e32 v4, 0, v4
	ds_write_b32 v74, v8 offset:6984
	v_sqrt_f32_e32 v9, v4
	s_nop 0
	v_add_u32_e32 v15, -1, v9
	v_fma_f32 v16, -v15, v9, v4
	v_cmp_ge_f32_e64 s[4:5], 0, v16
	v_add_u32_e32 v16, 1, v9
	s_nop 0
	v_cndmask_b32_e64 v15, v9, v15, s[4:5]
	v_fma_f32 v9, -v16, v9, v4
	v_cmp_lt_f32_e64 s[4:5], 0, v9
	s_nop 1
	v_cndmask_b32_e64 v9, v15, v16, s[4:5]
	s_nop 1
	v_mov_b32_e32 v4, v9
	v_mul_f32_e32 v4, v5, v4
	v_mul_f32_e32 v4, v37, v4
	ds_write_b32 v74, v4 offset:2760
	v_add_f32_e32 v4, v10, v12
	v_mul_f32_e32 v4, 0xbfb8aa3b, v4
	v_exp_f32_e32 v4, v4
	v_add_f32_e32 v5, v6, v13
	v_mul_f32_e32 v5, 0xbfb8aa3b, v5
	v_exp_f32_e32 v5, v5
	v_add_f32_e32 v4, 1.0, v4
	v_rcp_f32_e32 v4, v4
	v_add_f32_e32 v5, 1.0, v5
	v_rcp_f32_e32 v5, v5
	v_mul_f32_e32 v4, 0xc1000000, v4
	v_mul_f32_e32 v4, v14, v4
	v_mul_f32_e32 v6, 0x3fb8aa3b, v4
	v_add_f32_e32 v4, v4, v4
	v_mul_f32_e32 v4, 0x3fb8aa3b, v4
	v_exp_f32_e32 v4, v4
	v_exp_f32_e32 v6, v6
	v_sub_f32_e32 v4, 1.0, v4
	v_max_f32_e32 v4, 0, v4
	ds_write_b32 v74, v6 offset:7248
	v_sqrt_f32_e32 v8, v4
	s_nop 0
	v_add_u32_e32 v9, -1, v8
	v_fma_f32 v10, -v9, v8, v4
	v_cmp_ge_f32_e64 s[4:5], 0, v10
	v_add_u32_e32 v10, 1, v8
	s_nop 0
	v_cndmask_b32_e64 v9, v8, v9, s[4:5]
	v_fma_f32 v8, -v10, v8, v4
	v_cmp_lt_f32_e64 s[4:5], 0, v8
	s_nop 1
	v_cndmask_b32_e64 v8, v9, v10, s[4:5]
	s_nop 1
	v_mov_b32_e32 v4, v8
	v_mul_f32_e32 v4, v5, v4
	v_mul_f32_e32 v4, v33, v4
	ds_write_b32 v74, v4 offset:3024
	v_add_f32_e32 v4, v11, v12
	v_mul_f32_e32 v4, 0xbfb8aa3b, v4
	v_exp_f32_e32 v4, v4
	v_add_f32_e32 v5, v7, v13
	v_mul_f32_e32 v5, 0xbfb8aa3b, v5
	v_exp_f32_e32 v5, v5
	v_add_f32_e32 v4, 1.0, v4
	v_rcp_f32_e32 v4, v4
	v_add_f32_e32 v5, 1.0, v5
	v_rcp_f32_e32 v5, v5
	v_mul_f32_e32 v4, 0xc1000000, v4
	v_mul_f32_e32 v4, v14, v4
	v_mul_f32_e32 v6, 0x3fb8aa3b, v4
	v_add_f32_e32 v4, v4, v4
	v_mul_f32_e32 v4, 0x3fb8aa3b, v4
	v_exp_f32_e32 v4, v4
	v_exp_f32_e32 v6, v6
	v_lshl_add_u32 v14, v3, 2, v79
	v_sub_f32_e32 v4, 1.0, v4
	v_max_f32_e32 v4, 0, v4
	ds_write2_b32 v44, v30, v6 offset0:70 offset1:86
	v_sqrt_f32_e32 v7, v4
	s_nop 0
	v_add_u32_e32 v8, -1, v7
	v_fma_f32 v9, -v8, v7, v4
	v_cmp_ge_f32_e64 s[4:5], 0, v9
	v_add_u32_e32 v9, 1, v7
	s_nop 0
	v_cndmask_b32_e64 v8, v7, v8, s[4:5]
	v_fma_f32 v7, -v9, v7, v4
	v_cmp_lt_f32_e64 s[4:5], 0, v7
	s_nop 1
	v_cndmask_b32_e64 v7, v8, v9, s[4:5]
	s_nop 1
	v_mov_b32_e32 v4, v7
	v_mul_f32_e32 v4, v5, v4
	v_mul_f32_e32 v4, v29, v4
	ds_write2_b32 v66, v28, v4 offset0:38 offset1:54
	s_waitcnt lgkmcnt(0)
	s_barrier
; __device__ __forceinline__ void lds_barrier() { asm volatile("s_waitcnt lgkmcnt(0)" ::: "memory"); __builtin_amdgcn_s_barrier(); asm volatile("" ::: "memory"); }
; __device__ __forceinline__ void lru_item(const Params& p, int l, int item, LAS unsigned char* lds) {
;     ...
;     { float A = 1.f, H = 0.f;
; #pragma unroll
;       for (int i = 0; i < 16; ++i) { const float a = sa[i * 66 + lane], bt = xf[i * 66 + lane]; H = a * H + bt; A *= a; Ac[i] = A; Hl[i] = H; }
;       ct[(wid * 64 + lane) * 2] = A; ct[(wid * 64 + lane) * 2 + 1] = H; }
;     lds_barrier();
;     { float Ain = 1.f, Hin = 0.f;
;       for (int w = 0; w < wid; ++w) { const float aw = ct[(w * 64 + lane) * 2], hw = ct[(w * 64 + lane) * 2 + 1]; Hin = aw * Hin + hw; Ain *= aw; }
	v_add_u32_e32 v4, 0x1800, v14
	ds_read2_b32 v[22:23], v4 offset0:30 offset1:96
	ds_read_b32 v18, v80 offset:2304
	ds_read2_b32 v[6:7], v4 offset0:162 offset1:228
	v_add_u32_e32 v4, 0x800, v14
	ds_read2_b32 v[20:21], v4 offset0:130 offset1:196
	v_add_u32_e32 v4, 0x1c00, v14
	v_add_u32_e32 v5, 0xc00, v14
	ds_read2_b32 v[8:9], v4 offset0:38 offset1:104
	ds_read2_b32 v[12:13], v5 offset0:6 offset1:72
	s_waitcnt lgkmcnt(4)
	v_fmac_f32_e32 v18, 0, v23
	ds_read2_b32 v[46:47], v4 offset0:170 offset1:236
	ds_read2_b32 v[10:11], v5 offset0:138 offset1:204
	s_waitcnt lgkmcnt(4)
	v_fma_f32 v19, v18, v6, v20
	v_fmac_f32_e32 v21, v19, v7
	s_waitcnt lgkmcnt(2)
	v_fma_f32 v25, v21, v8, v12
	v_fmac_f32_e32 v13, v25, v9
	v_mul_f32_e32 v28, v23, v6
	s_waitcnt lgkmcnt(0)
	v_fma_f32 v17, v13, v46, v10
	v_add_u32_e32 v6, 0x2000, v14
	v_add_u32_e32 v10, 0x1000, v14
	ds_read2_b32 v[40:41], v6 offset0:46 offset1:112
	ds_read2_b32 v[4:5], v10 offset0:14 offset1:80
	ds_read2_b32 v[38:39], v6 offset0:178 offset1:244
	ds_read2_b32 v[42:43], v10 offset0:146 offset1:212
	v_fmac_f32_e32 v11, v17, v47
	v_mov_b32_e32 v6, v7
	v_mov_b32_e32 v26, v8
	s_waitcnt lgkmcnt(2)
	v_fma_f32 v15, v11, v40, v4
	v_fmac_f32_e32 v5, v15, v41
	v_mov_b32_e32 v29, v5
	s_waitcnt lgkmcnt(1)
	v_mov_b32_e32 v7, v38
	v_add_u32_e32 v4, 0x2400, v14
	v_pk_mul_f32 v[32:33], v[28:29], v[6:7]
	s_waitcnt lgkmcnt(0)
	v_mov_b32_e32 v27, v42
	ds_read2_b32 v[48:49], v4 offset0:54 offset1:120
	v_pk_mul_f32 v[36:37], v[32:33], v[26:27]
	v_pk_fma_f32 v[6:7], v[28:29], v[6:7], v[26:27]
	v_mov_b32_e32 v8, v9
	v_mov_b32_e32 v37, v7
	v_mov_b32_e32 v9, v39
	v_pk_mul_f32 v[26:27], v[36:37], v[8:9]
	v_mov_b32_e32 v42, v46
	v_add_u32_e32 v6, 0x1400, v14
	v_pk_mul_f32 v[30:31], v[26:27], v[42:43]
	v_pk_fma_f32 v[8:9], v[36:37], v[8:9], v[42:43]
	ds_read2_b32 v[50:51], v6 offset0:22 offset1:88
	ds_read2_b32 v[42:43], v4 offset0:186 offset1:252
	ds_read2_b32 v[44:45], v6 offset0:154 offset1:220
	ds_read_b32 v67, v14 offset:10488
	v_mov_b32_e32 v31, v9
	v_mov_b32_e32 v46, v47
	s_waitcnt lgkmcnt(4)
	v_mov_b32_e32 v47, v48
	v_pk_mul_f32 v[60:61], v[30:31], v[46:47]
	v_mov_b32_e32 v52, v40
	s_waitcnt lgkmcnt(3)
	v_mov_b32_e32 v53, v50
	v_pk_mul_f32 v[64:65], v[60:61], v[52:53]
	v_pk_fma_f32 v[52:53], v[30:31], v[46:47], v[52:53]
	v_mov_b32_e32 v40, v41
	v_mov_b32_e32 v65, v53
	v_mov_b32_e32 v41, v49
	v_pk_mul_f32 v[54:55], v[64:65], v[40:41]
	v_mov_b32_e32 v50, v38
	v_pk_mul_f32 v[58:59], v[54:55], v[50:51]
	v_pk_fma_f32 v[40:41], v[64:65], v[40:41], v[50:51]
	v_mov_b32_e32 v38, v39
	v_mov_b32_e32 v59, v41
	s_waitcnt lgkmcnt(2)
	v_mov_b32_e32 v39, v42
	v_pk_mul_f32 v[56:57], v[58:59], v[38:39]
	v_mov_b32_e32 v46, v48
	s_waitcnt lgkmcnt(1)
	v_mov_b32_e32 v47, v44
	v_pk_mul_f32 v[62:63], v[56:57], v[46:47]
	v_pk_fma_f32 v[46:47], v[58:59], v[38:39], v[46:47]
	v_mov_b32_e32 v38, v49
	v_mov_b32_e32 v63, v47
	v_mov_b32_e32 v39, v43
	v_pk_mul_f32 v[48:49], v[62:63], v[38:39]
	v_mov_b32_e32 v44, v42
	v_pk_mul_f32 v[50:51], v[48:49], v[44:45]
	v_pk_fma_f32 v[38:39], v[62:63], v[38:39], v[44:45]
	v_mov_b32_e32 v66, v43
	v_mov_b32_e32 v51, v39
	s_waitcnt lgkmcnt(0)
	v_pk_mul_f32 v[44:45], v[50:51], v[66:67]
	v_mov_b32_e32 v68, v67
	v_mov_b32_e32 v69, v22
	v_pk_mul_f32 v[42:43], v[44:45], v[68:69]
	v_pk_fma_f32 v[66:67], v[50:51], v[66:67], v[68:69]
	v_mul_f32_e32 v34, 0, v23
	v_mov_b32_e32 v43, v67
	ds_write_b64 v1, v[42:43]
	s_waitcnt lgkmcnt(0)
	s_barrier
	v_cmp_lt_i32_e32 vcc, 0, v0
	v_mov_b32_e32 v8, 1.0
	s_and_saveexec_b64 s[4:5], vcc
	s_cbranch_execz .LBB0_397
	v_readlane_b32 s6, v255, 9
	v_mov_b32_e32 v8, 1.0
	v_mov_b32_e32 v77, 0
	v_lshl_add_u32 v1, v3, 3, s6
	v_add_u32_e32 v10, -4, v1
	ds_read_b64 v[100:101], v10
	ds_read_b64 v[102:103], v10 offset:512
	ds_read_b64 v[104:105], v10 offset:1024
	ds_read_b64 v[106:107], v10 offset:1536
	ds_read_b64 v[108:109], v10 offset:2048
	ds_read_b64 v[110:111], v10 offset:2560
	ds_read_b64 v[112:113], v10 offset:3072
	v_readfirstlane_b32 s98, v0
	s_waitcnt lgkmcnt(0)
	v_mul_f32_e32 v8, v8, v100
	v_fma_f32 v77, v77, v100, v101
	s_cmp_lt_u32 s98, 2
	s_cbranch_scc1 .Llrupfx_done
	v_mul_f32_e32 v8, v8, v102
	v_fma_f32 v77, v77, v102, v103
	s_cmp_lt_u32 s98, 3
	s_cbranch_scc1 .Llrupfx_done
	v_mul_f32_e32 v8, v8, v104
	v_fma_f32 v77, v77, v104, v105
	s_cmp_lt_u32 s98, 4
	s_cbranch_scc1 .Llrupfx_done
	v_mul_f32_e32 v8, v8, v106
	v_fma_f32 v77, v77, v106, v107
	s_cmp_lt_u32 s98, 5
	s_cbranch_scc1 .Llrupfx_done
	v_mul_f32_e32 v8, v8, v108
	v_fma_f32 v77, v77, v108, v109
	s_cmp_lt_u32 s98, 6
	s_cbranch_scc1 .Llrupfx_done
	v_mul_f32_e32 v8, v8, v110
	v_fma_f32 v77, v77, v110, v111
	s_cmp_lt_u32 s98, 7
	s_cbranch_scc1 .Llrupfx_done
	v_mul_f32_e32 v8, v8, v112
	v_fma_f32 v77, v77, v112, v113
.Llrupfx_done:
	v_mul_f32_e32 v34, v23, v77
